# in-proj and gate-up epilogues: each lane computes 2 of the wave's 128 RMSNorm row factors (same instruction sequence) and lanes exchange them by ds_bpermute, instead of 8 per lane
# speedup vs baseline: 1.0224x; 1.0224x over previous
.LBB0_460:
	v_lshl_add_u32 v140, s27, 8, v146
	v_lshrrev_b32_e32 v190, 4, v197
	v_and_b32_e32 v191, 1, v190
	v_lshlrev_b32_e32 v191, 5, v191
	v_lshrrev_b32_e32 v192, 1, v190
	v_lshl_add_u32 v191, v192, 7, v191
	v_add_u32_e32 v192, v140, v191
	v_ashrrev_i32_e32 v193, 31, v192
	v_lshlrev_b64 v[192:193], 6, v[192:193]
	v_lshl_add_u64 v[192:193], s[42:43], 0, v[192:193]
	global_load_dwordx4 v[172:175], v[192:193], off
	global_load_dwordx4 v[176:179], v[192:193], off offset:16
	global_load_dwordx4 v[180:183], v[192:193], off offset:32
	global_load_dwordx4 v[184:187], v[192:193], off offset:48
	global_load_dwordx4 v[226:229], v[192:193], off offset:1024
	global_load_dwordx4 v[230:233], v[192:193], off offset:1040
	global_load_dwordx4 v[234:237], v[192:193], off offset:1056
	global_load_dwordx4 v[238:241], v[192:193], off offset:1072
	s_waitcnt vmcnt(0)
	v_add_f32_e32 v172, v172, v173
	v_add_f32_e32 v174, v174, v175
	v_add_f32_e32 v172, v172, v174
	v_add_f32_e32 v176, v176, v177
	v_add_f32_e32 v178, v178, v179
	v_add_f32_e32 v176, v176, v178
	v_add_f32_e32 v180, v180, v181
	v_add_f32_e32 v182, v182, v183
	v_add_f32_e32 v180, v180, v182
	v_add_f32_e32 v184, v184, v185
	v_add_f32_e32 v186, v186, v187
	v_add_f32_e32 v184, v184, v186
	v_add_f32_e32 v172, v172, v176
	v_add_f32_e32 v180, v180, v184
	v_add_f32_e32 v188, v172, v180
	v_add_f32_e32 v226, v226, v227
	v_add_f32_e32 v228, v228, v229
	v_add_f32_e32 v226, v226, v228
	v_add_f32_e32 v230, v230, v231
	v_add_f32_e32 v232, v232, v233
	v_add_f32_e32 v230, v230, v232
	v_add_f32_e32 v234, v234, v235
	v_add_f32_e32 v236, v236, v237
	v_add_f32_e32 v234, v234, v236
	v_add_f32_e32 v238, v238, v239
	v_add_f32_e32 v240, v240, v241
	v_add_f32_e32 v238, v238, v240
	v_add_f32_e32 v226, v226, v230
	v_add_f32_e32 v234, v234, v238
	v_add_f32_e32 v189, v226, v234
	v_fmamk_f32 v188, v188, 0x3a800000, v194
	v_mul_f32_e32 v172, 0x4f800000, v188
	v_cmp_gt_f32_e32 vcc, 0xf800000, v188
	s_nop 1
	v_cndmask_b32_e32 v188, v188, v172, vcc
	v_sqrt_f32_e32 v172, v188
	s_nop 0
	v_add_u32_e32 v173, -1, v172
	v_add_u32_e32 v174, 1, v172
	v_fma_f32 v175, -v173, v172, v188
	v_cmp_ge_f32_e64 s[4:5], 0, v175
	v_fma_f32 v175, -v174, v172, v188
	s_nop 0
	v_cndmask_b32_e64 v172, v172, v173, s[4:5]
	v_cmp_lt_f32_e64 s[4:5], 0, v175
	s_nop 1
	v_cndmask_b32_e64 v172, v172, v174, s[4:5]
	v_mul_f32_e32 v173, 0x37800000, v172
	v_cndmask_b32_e32 v172, v172, v173, vcc
	v_cmp_class_f32_e32 vcc, v188, v195
	s_nop 1
	v_cndmask_b32_e32 v188, v172, v188, vcc
	v_div_scale_f32 v172, s[4:5], v188, v188, 1.0
	v_rcp_f32_e32 v173, v172
	v_div_scale_f32 v174, vcc, 1.0, v188, 1.0
	v_fma_f32 v175, -v172, v173, 1.0
	v_fmac_f32_e32 v173, v175, v173
	v_mul_f32_e32 v175, v174, v173
	v_fma_f32 v242, -v172, v175, v174
	v_fmac_f32_e32 v175, v242, v173
	v_fma_f32 v172, -v172, v175, v174
	v_div_fmas_f32 v172, v172, v173, v175
	v_div_fixup_f32 v188, v172, v188, 1.0
	v_fmamk_f32 v189, v189, 0x3a800000, v194
	v_mul_f32_e32 v176, 0x4f800000, v189
	v_cmp_gt_f32_e32 vcc, 0xf800000, v189
	s_nop 1
	v_cndmask_b32_e32 v189, v189, v176, vcc
	v_sqrt_f32_e32 v176, v189
	s_nop 0
	v_add_u32_e32 v177, -1, v176
	v_add_u32_e32 v178, 1, v176
	v_fma_f32 v179, -v177, v176, v189
	v_cmp_ge_f32_e64 s[4:5], 0, v179
	v_fma_f32 v179, -v178, v176, v189
	s_nop 0
	v_cndmask_b32_e64 v176, v176, v177, s[4:5]
	v_cmp_lt_f32_e64 s[4:5], 0, v179
	s_nop 1
	v_cndmask_b32_e64 v176, v176, v178, s[4:5]
	v_mul_f32_e32 v177, 0x37800000, v176
	v_cndmask_b32_e32 v176, v176, v177, vcc
	v_cmp_class_f32_e32 vcc, v189, v195
	s_nop 1
	v_cndmask_b32_e32 v189, v176, v189, vcc
	v_div_scale_f32 v176, s[4:5], v189, v189, 1.0
	v_rcp_f32_e32 v177, v176
	v_div_scale_f32 v178, vcc, 1.0, v189, 1.0
	v_fma_f32 v179, -v176, v177, 1.0
	v_fmac_f32_e32 v177, v179, v177
	v_mul_f32_e32 v179, v178, v177
	v_fma_f32 v242, -v176, v179, v178
	v_fmac_f32_e32 v179, v242, v177
	v_fma_f32 v176, -v176, v179, v178
	v_div_fmas_f32 v176, v176, v177, v179
	v_div_fixup_f32 v189, v176, v189, 1.0
	v_and_b32_e32 v190, 15, v197
	v_lshlrev_b32_e32 v190, 2, v190
	v_add_u32_e32 v191, 64, v190
	v_add_u32_e32 v192, 128, v190
	v_add_u32_e32 v193, 192, v190
	ds_bpermute_b32 v244, v190, v188
	ds_bpermute_b32 v245, v190, v189
	ds_bpermute_b32 v246, v191, v188
	ds_bpermute_b32 v247, v191, v189
	ds_bpermute_b32 v248, v192, v188
	ds_bpermute_b32 v249, v192, v189
	ds_bpermute_b32 v250, v193, v188
	ds_bpermute_b32 v251, v193, v189
	s_waitcnt lgkmcnt(0)
	v_ashrrev_i32_e32 v141, 31, v140
	v_lshlrev_b64 v[144:145], 6, v[140:141]
	v_lshl_add_u64 v[142:143], s[42:43], 0, v[144:145]
	s_mov_b32 s4, 0xf800000
	v_mov_b64_e32 v[164:165], s[36:37]
	v_lshl_or_b32 v142, s26, 8, v148
	s_movk_i32 s33, 0xac7
	s_waitcnt lgkmcnt(0)
	s_nop 0
	s_nop 0
	s_movk_i32 s4, 0x1600
	v_mad_i64_i32 v[150:151], s[4:5], v140, s4, v[164:165]
	v_ashrrev_i32_e32 v143, 31, v142
	v_lshl_add_u64 v[150:151], v[142:143], 1, v[150:151]
	s_nop 1
	s_nop 1
	s_nop 1
	s_mov_b64 s[4:5], 0
	v_mov_b32_e32 v152, v244
	v_pk_mul_f32 v[128:129], v[128:129], v[152:153] op_sel_hi:[1,0]
	v_pk_mul_f32 v[126:127], v[126:127], v[152:153] op_sel_hi:[1,0]
	v_pk_mul_f32 v[154:155], v[124:125], v[152:153] op_sel_hi:[1,0]
	v_pk_mul_f32 v[124:125], v[122:123], v[152:153] op_sel_hi:[1,0]
	v_pk_mul_f32 v[114:115], v[114:115], v[152:153] op_sel_hi:[1,0]
	v_pk_mul_f32 v[120:121], v[120:121], v[152:153] op_sel_hi:[1,0]
	v_pk_mul_f32 v[118:119], v[118:119], v[152:153] op_sel_hi:[1,0]
	v_pk_mul_f32 v[116:117], v[116:117], v[152:153] op_sel_hi:[1,0]
	v_cvt_pk_bf16_f32 v122, v126, v127
	v_cvt_pk_bf16_f32 v123, v128, v129
	v_cvt_pk_bf16_f32 v124, v124, v125
	v_cvt_pk_bf16_f32 v125, v154, v155
	v_cvt_pk_bf16_f32 v128, v114, v115
	v_cvt_pk_bf16_f32 v126, v118, v119
	v_cvt_pk_bf16_f32 v127, v120, v121
	v_cvt_pk_bf16_f32 v129, v116, v117
	global_store_dwordx4 v[150:151], v[122:125], off
	global_store_dwordx4 v[150:151], v[126:129], off offset:256
	s_nop 1
	v_or_b32_e32 v128, 0x80, v142
	v_cmp_lt_i32_e32 vcc, s33, v128
	s_and_saveexec_b64 s[26:27], vcc
	s_xor_b64 s[30:31], exec, s[26:27]
	s_movk_i32 s4, 0xac8
	v_cmp_eq_u32_e32 vcc, s4, v128
	s_and_b64 s[4:5], vcc, exec
	s_or_saveexec_b64 s[30:31], s[30:31]
	v_lshl_add_u64 v[122:123], s[38:39], 0, v[144:145]
	v_mov_b64_e32 v[124:125], 40
	v_mov_b64_e32 v[126:127], 44
	s_xor_b64 exec, exec, s[30:31]
	s_cbranch_execz .LBB0_466
	s_movk_i32 s26, 0xac0
	v_cmp_eq_u32_e32 vcc, s26, v128
	s_mov_b64 s[54:55], s[4:5]
	s_and_saveexec_b64 s[56:57], vcc
	s_cbranch_execz .LBB0_465
	global_store_dwordx4 v[122:123], v[118:121], off
	global_store_dwordx2 v[122:123], v[114:115], off offset:16
	s_or_b64 s[54:55], s[4:5], exec
	v_mov_b32_e32 v119, v117
	v_mov_b32_e32 v118, v116

.LBB0_468:
	s_or_b64 exec, exec, s[30:31]
	v_or_b32_e32 v144, 16, v140
	v_ashrrev_i32_e32 v145, 31, v144
	v_lshlrev_b64 v[114:115], 6, v[144:145]
	v_lshl_add_u64 v[150:151], s[42:43], 0, v[114:115]
	s_nop 0
	s_mov_b32 s4, 0xf800000
	s_waitcnt lgkmcnt(0)
	s_nop 0
	s_nop 0
	s_movk_i32 s4, 0x1600
	s_nop 0
	v_mov_b64_e32 v[116:117], s[36:37]
	v_mad_i64_i32 v[116:117], s[4:5], v144, s4, v[116:117]
	v_lshl_add_u64 v[116:117], v[142:143], 1, v[116:117]
	s_nop 0
	s_nop 1
	s_nop 1
	s_mov_b64 s[4:5], 0
	v_mov_b32_e32 v118, v245
	v_pk_mul_f32 v[112:113], v[112:113], v[118:119] op_sel_hi:[1,0]
	v_pk_mul_f32 v[110:111], v[110:111], v[118:119] op_sel_hi:[1,0]
	v_pk_mul_f32 v[120:121], v[108:109], v[118:119] op_sel_hi:[1,0]
	v_pk_mul_f32 v[108:109], v[106:107], v[118:119] op_sel_hi:[1,0]
	v_pk_mul_f32 v[104:105], v[104:105], v[118:119] op_sel_hi:[1,0]
	v_pk_mul_f32 v[102:103], v[102:103], v[118:119] op_sel_hi:[1,0]
	v_pk_mul_f32 v[100:101], v[100:101], v[118:119] op_sel_hi:[1,0]
	v_pk_mul_f32 v[98:99], v[98:99], v[118:119] op_sel_hi:[1,0]
	v_cvt_pk_bf16_f32 v106, v110, v111
	v_cvt_pk_bf16_f32 v107, v112, v113
	v_cvt_pk_bf16_f32 v108, v108, v109
	v_cvt_pk_bf16_f32 v109, v120, v121
	v_cmp_lt_i32_e32 vcc, s33, v128
	v_cvt_pk_bf16_f32 v110, v102, v103
	v_cvt_pk_bf16_f32 v111, v104, v105
	v_cvt_pk_bf16_f32 v112, v98, v99
	v_cvt_pk_bf16_f32 v113, v100, v101
	global_store_dwordx4 v[116:117], v[106:109], off
	global_store_dwordx4 v[116:117], v[110:113], off offset:256
	s_and_saveexec_b64 s[26:27], vcc
	s_xor_b64 s[30:31], exec, s[26:27]
	s_movk_i32 s4, 0xac8
	v_cmp_eq_u32_e32 vcc, s4, v128
	s_and_b64 s[4:5], vcc, exec
	s_or_saveexec_b64 s[30:31], s[30:31]
	v_lshl_add_u64 v[106:107], s[38:39], 0, v[114:115]
	v_mov_b64_e32 v[108:109], 40
	v_mov_b64_e32 v[110:111], 44
	s_xor_b64 exec, exec, s[30:31]
	s_cbranch_execz .LBB0_474
	s_movk_i32 s26, 0xac0
	v_cmp_eq_u32_e32 vcc, s26, v128
	s_mov_b64 s[54:55], s[4:5]
	s_and_saveexec_b64 s[56:57], vcc
	s_cbranch_execz .LBB0_473
	global_store_dwordx4 v[106:107], v[102:105], off
	global_store_dwordx2 v[106:107], v[98:99], off offset:16
	s_or_b64 s[54:55], s[4:5], exec
	v_mov_b32_e32 v103, v101
	v_mov_b32_e32 v102, v100

.LBB0_476:
	s_or_b64 exec, exec, s[30:31]
	v_or_b32_e32 v116, 32, v140
	v_ashrrev_i32_e32 v117, 31, v116
	v_lshlrev_b64 v[98:99], 6, v[116:117]
	v_lshl_add_u64 v[112:113], s[42:43], 0, v[98:99]
	s_nop 0
	s_mov_b32 s4, 0xf800000
	s_waitcnt lgkmcnt(0)
	s_nop 0
	s_nop 0
	s_movk_i32 s4, 0x1600
	s_nop 0
	v_mov_b64_e32 v[100:101], s[36:37]
	v_mad_i64_i32 v[100:101], s[4:5], v116, s4, v[100:101]
	v_lshl_add_u64 v[100:101], v[142:143], 1, v[100:101]
	s_nop 0
	s_nop 1
	s_nop 1
	s_mov_b64 s[4:5], 0
	v_mov_b32_e32 v102, v246
	v_pk_mul_f32 v[96:97], v[96:97], v[102:103] op_sel_hi:[1,0]
	v_pk_mul_f32 v[94:95], v[94:95], v[102:103] op_sel_hi:[1,0]
	v_pk_mul_f32 v[104:105], v[92:93], v[102:103] op_sel_hi:[1,0]
	v_pk_mul_f32 v[92:93], v[90:91], v[102:103] op_sel_hi:[1,0]
	v_pk_mul_f32 v[88:89], v[88:89], v[102:103] op_sel_hi:[1,0]
	v_pk_mul_f32 v[86:87], v[86:87], v[102:103] op_sel_hi:[1,0]
	v_pk_mul_f32 v[84:85], v[84:85], v[102:103] op_sel_hi:[1,0]
	v_pk_mul_f32 v[82:83], v[82:83], v[102:103] op_sel_hi:[1,0]
	v_cvt_pk_bf16_f32 v90, v94, v95
	v_cvt_pk_bf16_f32 v91, v96, v97
	v_cvt_pk_bf16_f32 v92, v92, v93
	v_cvt_pk_bf16_f32 v93, v104, v105
	v_cmp_lt_i32_e32 vcc, s33, v128
	v_cvt_pk_bf16_f32 v94, v86, v87
	v_cvt_pk_bf16_f32 v95, v88, v89
	v_cvt_pk_bf16_f32 v96, v82, v83
	v_cvt_pk_bf16_f32 v97, v84, v85
	global_store_dwordx4 v[100:101], v[90:93], off
	global_store_dwordx4 v[100:101], v[94:97], off offset:256
	s_and_saveexec_b64 s[26:27], vcc
	s_xor_b64 s[30:31], exec, s[26:27]
	s_movk_i32 s4, 0xac8
	v_cmp_eq_u32_e32 vcc, s4, v128
	s_and_b64 s[4:5], vcc, exec
	s_or_saveexec_b64 s[30:31], s[30:31]
	v_lshl_add_u64 v[90:91], s[38:39], 0, v[98:99]
	v_mov_b64_e32 v[92:93], 40
	v_mov_b64_e32 v[94:95], 44
	s_xor_b64 exec, exec, s[30:31]
	s_cbranch_execz .LBB0_482
	s_movk_i32 s26, 0xac0
	v_cmp_eq_u32_e32 vcc, s26, v128
	s_mov_b64 s[54:55], s[4:5]
	s_and_saveexec_b64 s[56:57], vcc
	s_cbranch_execz .LBB0_481
	global_store_dwordx4 v[90:91], v[86:89], off
	global_store_dwordx2 v[90:91], v[82:83], off offset:16
	s_or_b64 s[54:55], s[4:5], exec
	v_mov_b32_e32 v87, v85
	v_mov_b32_e32 v86, v84

.LBB0_484:
	s_or_b64 exec, exec, s[30:31]
	v_or_b32_e32 v100, 48, v140
	v_ashrrev_i32_e32 v101, 31, v100
	v_lshlrev_b64 v[82:83], 6, v[100:101]
	v_lshl_add_u64 v[96:97], s[42:43], 0, v[82:83]
	s_nop 0
	s_mov_b32 s4, 0xf800000
	s_waitcnt lgkmcnt(0)
	s_nop 0
	s_nop 0
	s_movk_i32 s4, 0x1600
	s_nop 0
	v_mov_b64_e32 v[84:85], s[36:37]
	v_mad_i64_i32 v[84:85], s[4:5], v100, s4, v[84:85]
	v_lshl_add_u64 v[84:85], v[142:143], 1, v[84:85]
	s_nop 0
	s_nop 1
	s_nop 1
	s_mov_b64 s[4:5], 0
	v_mov_b32_e32 v86, v247
	v_pk_mul_f32 v[80:81], v[80:81], v[86:87] op_sel_hi:[1,0]
	v_pk_mul_f32 v[78:79], v[78:79], v[86:87] op_sel_hi:[1,0]
	v_pk_mul_f32 v[88:89], v[76:77], v[86:87] op_sel_hi:[1,0]
	v_pk_mul_f32 v[76:77], v[74:75], v[86:87] op_sel_hi:[1,0]
	v_pk_mul_f32 v[72:73], v[72:73], v[86:87] op_sel_hi:[1,0]
	v_pk_mul_f32 v[70:71], v[70:71], v[86:87] op_sel_hi:[1,0]
	v_pk_mul_f32 v[68:69], v[68:69], v[86:87] op_sel_hi:[1,0]
	v_pk_mul_f32 v[66:67], v[66:67], v[86:87] op_sel_hi:[1,0]
	v_cvt_pk_bf16_f32 v74, v78, v79
	v_cvt_pk_bf16_f32 v75, v80, v81
	v_cvt_pk_bf16_f32 v76, v76, v77
	v_cvt_pk_bf16_f32 v77, v88, v89
	v_cmp_lt_i32_e32 vcc, s33, v128
	v_cvt_pk_bf16_f32 v78, v70, v71
	v_cvt_pk_bf16_f32 v79, v72, v73
	v_cvt_pk_bf16_f32 v80, v66, v67
	v_cvt_pk_bf16_f32 v81, v68, v69
	global_store_dwordx4 v[84:85], v[74:77], off
	global_store_dwordx4 v[84:85], v[78:81], off offset:256
	s_and_saveexec_b64 s[26:27], vcc
	s_xor_b64 s[30:31], exec, s[26:27]
	s_movk_i32 s4, 0xac8
	v_cmp_eq_u32_e32 vcc, s4, v128
	s_and_b64 s[4:5], vcc, exec
	s_or_saveexec_b64 s[30:31], s[30:31]
	v_lshl_add_u64 v[74:75], s[38:39], 0, v[82:83]
	v_mov_b64_e32 v[76:77], 40
	v_mov_b64_e32 v[78:79], 44
	s_xor_b64 exec, exec, s[30:31]
	s_cbranch_execz .LBB0_490
	s_movk_i32 s26, 0xac0
	v_cmp_eq_u32_e32 vcc, s26, v128
	s_mov_b64 s[54:55], s[4:5]
	s_and_saveexec_b64 s[56:57], vcc
	s_cbranch_execz .LBB0_489
	global_store_dwordx4 v[74:75], v[70:73], off
	global_store_dwordx2 v[74:75], v[66:67], off offset:16
	s_or_b64 s[54:55], s[4:5], exec
	v_mov_b32_e32 v71, v69
	v_mov_b32_e32 v70, v68

.LBB0_492:
	s_or_b64 exec, exec, s[30:31]
	v_add_u32_e32 v84, 0x80, v140
	v_ashrrev_i32_e32 v85, 31, v84
	v_lshlrev_b64 v[66:67], 6, v[84:85]
	v_lshl_add_u64 v[80:81], s[42:43], 0, v[66:67]
	s_nop 0
	s_mov_b32 s4, 0xf800000
	s_waitcnt lgkmcnt(0)
	s_nop 0
	s_nop 0
	s_movk_i32 s4, 0x1600
	s_nop 0
	v_mov_b64_e32 v[68:69], s[36:37]
	v_mad_i64_i32 v[68:69], s[4:5], v84, s4, v[68:69]
	v_lshl_add_u64 v[68:69], v[142:143], 1, v[68:69]
	s_nop 0
	s_nop 1
	s_nop 1
	s_mov_b64 s[4:5], 0
	v_mov_b32_e32 v70, v248
	v_pk_mul_f32 v[62:63], v[62:63], v[70:71] op_sel_hi:[1,0]
	v_pk_mul_f32 v[60:61], v[60:61], v[70:71] op_sel_hi:[1,0]
	v_pk_mul_f32 v[72:73], v[58:59], v[70:71] op_sel_hi:[1,0]
	v_pk_mul_f32 v[58:59], v[56:57], v[70:71] op_sel_hi:[1,0]
	v_pk_mul_f32 v[54:55], v[54:55], v[70:71] op_sel_hi:[1,0]
	v_pk_mul_f32 v[52:53], v[52:53], v[70:71] op_sel_hi:[1,0]
	v_pk_mul_f32 v[50:51], v[50:51], v[70:71] op_sel_hi:[1,0]
	v_pk_mul_f32 v[48:49], v[48:49], v[70:71] op_sel_hi:[1,0]
	v_cvt_pk_bf16_f32 v56, v60, v61
	v_cvt_pk_bf16_f32 v57, v62, v63
	v_cvt_pk_bf16_f32 v58, v58, v59
	v_cvt_pk_bf16_f32 v59, v72, v73
	v_cmp_lt_i32_e32 vcc, s33, v128
	v_cvt_pk_bf16_f32 v60, v52, v53
	v_cvt_pk_bf16_f32 v61, v54, v55
	v_cvt_pk_bf16_f32 v62, v48, v49
	v_cvt_pk_bf16_f32 v63, v50, v51
	global_store_dwordx4 v[68:69], v[56:59], off
	global_store_dwordx4 v[68:69], v[60:63], off offset:256
	s_and_saveexec_b64 s[26:27], vcc
	s_xor_b64 s[30:31], exec, s[26:27]
	s_movk_i32 s4, 0xac8
	v_cmp_eq_u32_e32 vcc, s4, v128
	s_and_b64 s[4:5], vcc, exec
	s_or_saveexec_b64 s[30:31], s[30:31]
	v_lshl_add_u64 v[56:57], s[38:39], 0, v[66:67]
	v_mov_b64_e32 v[58:59], 40
	v_mov_b64_e32 v[60:61], 44
	s_xor_b64 exec, exec, s[30:31]
	s_cbranch_execz .LBB0_498
	s_movk_i32 s26, 0xac0
	v_cmp_eq_u32_e32 vcc, s26, v128
	s_mov_b64 s[54:55], s[4:5]
	s_and_saveexec_b64 s[56:57], vcc
	s_cbranch_execz .LBB0_497
	global_store_dwordx4 v[56:57], v[52:55], off
	global_store_dwordx2 v[56:57], v[48:49], off offset:16
	s_or_b64 s[54:55], s[4:5], exec
	v_mov_b32_e32 v53, v51
	v_mov_b32_e32 v52, v50

.LBB0_500:
	s_or_b64 exec, exec, s[30:31]
	v_add_u32_e32 v62, 0x90, v140
	v_ashrrev_i32_e32 v63, 31, v62
	v_lshlrev_b64 v[48:49], 6, v[62:63]
	v_lshl_add_u64 v[66:67], s[42:43], 0, v[48:49]
	s_nop 0
	s_mov_b32 s4, 0xf800000
	s_waitcnt lgkmcnt(0)
	s_nop 0
	s_nop 0
	s_movk_i32 s4, 0x1600
	s_nop 0
	v_mov_b64_e32 v[50:51], s[36:37]
	v_mad_i64_i32 v[50:51], s[4:5], v62, s4, v[50:51]
	v_lshl_add_u64 v[50:51], v[142:143], 1, v[50:51]
	s_nop 0
	s_nop 1
	s_nop 1
	s_mov_b64 s[4:5], 0
	v_mov_b32_e32 v52, v249
	v_pk_mul_f32 v[46:47], v[46:47], v[52:53] op_sel_hi:[1,0]
	v_pk_mul_f32 v[44:45], v[44:45], v[52:53] op_sel_hi:[1,0]
	v_pk_mul_f32 v[54:55], v[42:43], v[52:53] op_sel_hi:[1,0]
	v_pk_mul_f32 v[42:43], v[40:41], v[52:53] op_sel_hi:[1,0]
	v_pk_mul_f32 v[38:39], v[38:39], v[52:53] op_sel_hi:[1,0]
	v_pk_mul_f32 v[36:37], v[36:37], v[52:53] op_sel_hi:[1,0]
	v_pk_mul_f32 v[34:35], v[34:35], v[52:53] op_sel_hi:[1,0]
	v_pk_mul_f32 v[32:33], v[32:33], v[52:53] op_sel_hi:[1,0]
	v_cvt_pk_bf16_f32 v40, v44, v45
	v_cvt_pk_bf16_f32 v41, v46, v47
	v_cvt_pk_bf16_f32 v42, v42, v43
	v_cvt_pk_bf16_f32 v43, v54, v55
	v_cmp_lt_i32_e32 vcc, s33, v128
	v_cvt_pk_bf16_f32 v44, v36, v37
	v_cvt_pk_bf16_f32 v45, v38, v39
	v_cvt_pk_bf16_f32 v46, v32, v33
	v_cvt_pk_bf16_f32 v47, v34, v35
	global_store_dwordx4 v[50:51], v[40:43], off
	global_store_dwordx4 v[50:51], v[44:47], off offset:256
	s_and_saveexec_b64 s[26:27], vcc
	s_xor_b64 s[30:31], exec, s[26:27]
	s_movk_i32 s4, 0xac8
	v_cmp_eq_u32_e32 vcc, s4, v128
	s_and_b64 s[4:5], vcc, exec
	s_or_saveexec_b64 s[30:31], s[30:31]
	v_lshl_add_u64 v[40:41], s[38:39], 0, v[48:49]
	v_mov_b64_e32 v[42:43], 40
	v_mov_b64_e32 v[44:45], 44
	s_xor_b64 exec, exec, s[30:31]
	s_cbranch_execz .LBB0_506
	s_movk_i32 s26, 0xac0
	v_cmp_eq_u32_e32 vcc, s26, v128
	s_mov_b64 s[54:55], s[4:5]
	s_and_saveexec_b64 s[56:57], vcc
	s_cbranch_execz .LBB0_505
	global_store_dwordx4 v[40:41], v[36:39], off
	global_store_dwordx2 v[40:41], v[32:33], off offset:16
	s_or_b64 s[54:55], s[4:5], exec
	v_mov_b32_e32 v37, v35
	v_mov_b32_e32 v36, v34

.LBB0_508:
	s_or_b64 exec, exec, s[30:31]
	v_add_u32_e32 v50, 0xa0, v140
	v_ashrrev_i32_e32 v51, 31, v50
	v_lshlrev_b64 v[32:33], 6, v[50:51]
	v_lshl_add_u64 v[46:47], s[42:43], 0, v[32:33]
	s_nop 0
	s_mov_b32 s4, 0xf800000
	s_waitcnt lgkmcnt(0)
	s_nop 0
	s_nop 0
	s_movk_i32 s4, 0x1600
	s_nop 0
	v_mov_b64_e32 v[34:35], s[36:37]
	v_mad_i64_i32 v[34:35], s[4:5], v50, s4, v[34:35]
	v_lshl_add_u64 v[34:35], v[142:143], 1, v[34:35]
	s_nop 0
	s_nop 1
	s_nop 1
	s_mov_b64 s[4:5], 0
	v_mov_b32_e32 v36, v250
	v_pk_mul_f32 v[30:31], v[30:31], v[36:37] op_sel_hi:[1,0]
	v_pk_mul_f32 v[28:29], v[28:29], v[36:37] op_sel_hi:[1,0]
	v_pk_mul_f32 v[38:39], v[26:27], v[36:37] op_sel_hi:[1,0]
	v_pk_mul_f32 v[26:27], v[24:25], v[36:37] op_sel_hi:[1,0]
	v_pk_mul_f32 v[22:23], v[22:23], v[36:37] op_sel_hi:[1,0]
	v_pk_mul_f32 v[20:21], v[20:21], v[36:37] op_sel_hi:[1,0]
	v_pk_mul_f32 v[18:19], v[18:19], v[36:37] op_sel_hi:[1,0]
	v_pk_mul_f32 v[16:17], v[16:17], v[36:37] op_sel_hi:[1,0]
	v_cvt_pk_bf16_f32 v24, v28, v29
	v_cvt_pk_bf16_f32 v25, v30, v31
	v_cvt_pk_bf16_f32 v26, v26, v27
	v_cvt_pk_bf16_f32 v27, v38, v39
	v_cmp_lt_i32_e32 vcc, s33, v128
	v_cvt_pk_bf16_f32 v28, v20, v21
	v_cvt_pk_bf16_f32 v29, v22, v23
	v_cvt_pk_bf16_f32 v30, v16, v17
	v_cvt_pk_bf16_f32 v31, v18, v19
	global_store_dwordx4 v[34:35], v[24:27], off
	global_store_dwordx4 v[34:35], v[28:31], off offset:256
	s_and_saveexec_b64 s[26:27], vcc
	s_xor_b64 s[30:31], exec, s[26:27]
	s_movk_i32 s4, 0xac8
	v_cmp_eq_u32_e32 vcc, s4, v128
	s_and_b64 s[4:5], vcc, exec
	s_or_saveexec_b64 s[30:31], s[30:31]
	v_lshl_add_u64 v[24:25], s[38:39], 0, v[32:33]
	v_mov_b64_e32 v[26:27], 40
	v_mov_b64_e32 v[28:29], 44
	s_xor_b64 exec, exec, s[30:31]
	s_cbranch_execz .LBB0_514
	s_movk_i32 s26, 0xac0
	v_cmp_eq_u32_e32 vcc, s26, v128
	s_mov_b64 s[54:55], s[4:5]
	s_and_saveexec_b64 s[56:57], vcc
	s_cbranch_execz .LBB0_513
	global_store_dwordx4 v[24:25], v[20:23], off
	global_store_dwordx2 v[24:25], v[16:17], off offset:16
	s_or_b64 s[54:55], s[4:5], exec
	v_mov_b32_e32 v21, v19
	v_mov_b32_e32 v20, v18

.LBB0_516:
	s_or_b64 exec, exec, s[30:31]
	v_add_u32_e32 v16, 0xb0, v140
	v_ashrrev_i32_e32 v17, 31, v16
	v_mov_b64_e32 v[18:19], s[36:37]
	s_movk_i32 s4, 0x1600
	v_mad_i64_i32 v[18:19], s[4:5], v16, s4, v[18:19]
	v_lshlrev_b64 v[16:17], 6, v[16:17]
	v_lshl_add_u64 v[32:33], s[42:43], 0, v[16:17]
	s_nop 0
	s_mov_b32 s4, 0xf800000
	v_lshl_add_u64 v[18:19], v[142:143], 1, v[18:19]
	s_waitcnt lgkmcnt(0)
	s_nop 0
	s_nop 0
	s_nop 0
	s_nop 0
	s_nop 0
	s_nop 0
	s_nop 0
	s_nop 1
	s_nop 1
	s_mov_b64 s[4:5], 0
	v_mov_b32_e32 v20, v251
	v_pk_mul_f32 v[14:15], v[14:15], v[20:21] op_sel_hi:[1,0]
	v_pk_mul_f32 v[12:13], v[12:13], v[20:21] op_sel_hi:[1,0]
	v_pk_mul_f32 v[22:23], v[10:11], v[20:21] op_sel_hi:[1,0]
	v_pk_mul_f32 v[10:11], v[8:9], v[20:21] op_sel_hi:[1,0]
	v_cvt_pk_bf16_f32 v8, v12, v13
	v_cvt_pk_bf16_f32 v9, v14, v15
	v_cvt_pk_bf16_f32 v10, v10, v11
	v_cvt_pk_bf16_f32 v11, v22, v23
	v_pk_mul_f32 v[6:7], v[6:7], v[20:21] op_sel_hi:[1,0]
	v_pk_mul_f32 v[4:5], v[4:5], v[20:21] op_sel_hi:[1,0]
	v_pk_mul_f32 v[2:3], v[2:3], v[20:21] op_sel_hi:[1,0]
	v_pk_mul_f32 v[0:1], v[0:1], v[20:21] op_sel_hi:[1,0]
	global_store_dwordx4 v[18:19], v[8:11], off
	v_cmp_lt_i32_e32 vcc, s33, v128
	s_nop 0
	v_cvt_pk_bf16_f32 v8, v4, v5
	v_cvt_pk_bf16_f32 v9, v6, v7
	v_cvt_pk_bf16_f32 v10, v0, v1
	v_cvt_pk_bf16_f32 v11, v2, v3
	global_store_dwordx4 v[18:19], v[8:11], off offset:256
	s_and_saveexec_b64 s[26:27], vcc
	s_xor_b64 s[30:31], exec, s[26:27]
	s_movk_i32 s4, 0xac8
	v_cmp_eq_u32_e32 vcc, s4, v128
	s_and_b64 s[4:5], vcc, exec
	s_or_saveexec_b64 s[30:31], s[30:31]
	v_lshl_add_u64 v[8:9], s[38:39], 0, v[16:17]
	v_mov_b64_e32 v[10:11], 40
	v_mov_b64_e32 v[12:13], 44
	s_xor_b64 exec, exec, s[30:31]
	s_cbranch_execz .LBB0_523
	s_movk_i32 s26, 0xac0
	v_cmp_eq_u32_e32 vcc, s26, v128
	s_mov_b64 s[54:55], s[4:5]
	s_and_saveexec_b64 s[56:57], vcc
	s_cbranch_execz .LBB0_521
	global_store_dwordx4 v[8:9], v[4:7], off
	global_store_dwordx2 v[8:9], v[0:1], off offset:16
	s_or_b64 s[54:55], s[4:5], exec
	v_mov_b32_e32 v5, v3
	v_mov_b32_e32 v4, v2

.LBB0_1255:
	v_lshl_add_u32 v140, s27, 8, v144
	v_lshrrev_b32_e32 v190, 4, v197
	v_and_b32_e32 v191, 1, v190
	v_lshlrev_b32_e32 v191, 5, v191
	v_lshrrev_b32_e32 v192, 1, v190
	v_lshl_add_u32 v191, v192, 7, v191
	v_add_u32_e32 v192, v140, v191
	v_ashrrev_i32_e32 v193, 31, v192
	v_lshlrev_b64 v[192:193], 6, v[192:193]
	v_lshl_add_u64 v[192:193], s[30:31], 0, v[192:193]
	global_load_dwordx4 v[172:175], v[192:193], off
	global_load_dwordx4 v[176:179], v[192:193], off offset:16
	global_load_dwordx4 v[180:183], v[192:193], off offset:32
	global_load_dwordx4 v[184:187], v[192:193], off offset:48
	global_load_dwordx4 v[226:229], v[192:193], off offset:1024
	global_load_dwordx4 v[230:233], v[192:193], off offset:1040
	global_load_dwordx4 v[234:237], v[192:193], off offset:1056
	global_load_dwordx4 v[238:241], v[192:193], off offset:1072
	s_waitcnt vmcnt(0)
	v_add_f32_e32 v172, v172, v173
	v_add_f32_e32 v174, v174, v175
	v_add_f32_e32 v172, v172, v174
	v_add_f32_e32 v176, v176, v177
	v_add_f32_e32 v178, v178, v179
	v_add_f32_e32 v176, v176, v178
	v_add_f32_e32 v180, v180, v181
	v_add_f32_e32 v182, v182, v183
	v_add_f32_e32 v180, v180, v182
	v_add_f32_e32 v184, v184, v185
	v_add_f32_e32 v186, v186, v187
	v_add_f32_e32 v184, v184, v186
	v_add_f32_e32 v172, v172, v176
	v_add_f32_e32 v180, v180, v184
	v_add_f32_e32 v188, v172, v180
	v_add_f32_e32 v226, v226, v227
	v_add_f32_e32 v228, v228, v229
	v_add_f32_e32 v226, v226, v228
	v_add_f32_e32 v230, v230, v231
	v_add_f32_e32 v232, v232, v233
	v_add_f32_e32 v230, v230, v232
	v_add_f32_e32 v234, v234, v235
	v_add_f32_e32 v236, v236, v237
	v_add_f32_e32 v234, v234, v236
	v_add_f32_e32 v238, v238, v239
	v_add_f32_e32 v240, v240, v241
	v_add_f32_e32 v238, v238, v240
	v_add_f32_e32 v226, v226, v230
	v_add_f32_e32 v234, v234, v238
	v_add_f32_e32 v189, v226, v234
	v_fmamk_f32 v188, v188, 0x3a800000, v194
	v_mul_f32_e32 v172, 0x4f800000, v188
	v_cmp_gt_f32_e32 vcc, 0xf800000, v188
	s_nop 1
	v_cndmask_b32_e32 v188, v188, v172, vcc
	v_sqrt_f32_e32 v172, v188
	s_nop 0
	v_add_u32_e32 v173, -1, v172
	v_add_u32_e32 v174, 1, v172
	v_fma_f32 v175, -v173, v172, v188
	v_cmp_ge_f32_e64 s[0:1], 0, v175
	v_fma_f32 v175, -v174, v172, v188
	s_nop 0
	v_cndmask_b32_e64 v172, v172, v173, s[0:1]
	v_cmp_lt_f32_e64 s[0:1], 0, v175
	s_nop 1
	v_cndmask_b32_e64 v172, v172, v174, s[0:1]
	v_mul_f32_e32 v173, 0x37800000, v172
	v_cndmask_b32_e32 v172, v172, v173, vcc
	v_cmp_class_f32_e32 vcc, v188, v195
	s_nop 1
	v_cndmask_b32_e32 v188, v172, v188, vcc
	v_div_scale_f32 v172, s[0:1], v188, v188, 1.0
	v_rcp_f32_e32 v173, v172
	v_div_scale_f32 v174, vcc, 1.0, v188, 1.0
	v_fma_f32 v175, -v172, v173, 1.0
	v_fmac_f32_e32 v173, v175, v173
	v_mul_f32_e32 v175, v174, v173
	v_fma_f32 v242, -v172, v175, v174
	v_fmac_f32_e32 v175, v242, v173
	v_fma_f32 v172, -v172, v175, v174
	v_div_fmas_f32 v172, v172, v173, v175
	v_div_fixup_f32 v188, v172, v188, 1.0
	v_fmamk_f32 v189, v189, 0x3a800000, v194
	v_mul_f32_e32 v176, 0x4f800000, v189
	v_cmp_gt_f32_e32 vcc, 0xf800000, v189
	s_nop 1
	v_cndmask_b32_e32 v189, v189, v176, vcc
	v_sqrt_f32_e32 v176, v189
	s_nop 0
	v_add_u32_e32 v177, -1, v176
	v_add_u32_e32 v178, 1, v176
	v_fma_f32 v179, -v177, v176, v189
	v_cmp_ge_f32_e64 s[0:1], 0, v179
	v_fma_f32 v179, -v178, v176, v189
	s_nop 0
	v_cndmask_b32_e64 v176, v176, v177, s[0:1]
	v_cmp_lt_f32_e64 s[0:1], 0, v179
	s_nop 1
	v_cndmask_b32_e64 v176, v176, v178, s[0:1]
	v_mul_f32_e32 v177, 0x37800000, v176
	v_cndmask_b32_e32 v176, v176, v177, vcc
	v_cmp_class_f32_e32 vcc, v189, v195
	s_nop 1
	v_cndmask_b32_e32 v189, v176, v189, vcc
	v_div_scale_f32 v176, s[0:1], v189, v189, 1.0
	v_rcp_f32_e32 v177, v176
	v_div_scale_f32 v178, vcc, 1.0, v189, 1.0
	v_fma_f32 v179, -v176, v177, 1.0
	v_fmac_f32_e32 v177, v179, v177
	v_mul_f32_e32 v179, v178, v177
	v_fma_f32 v242, -v176, v179, v178
	v_fmac_f32_e32 v179, v242, v177
	v_fma_f32 v176, -v176, v179, v178
	v_div_fmas_f32 v176, v176, v177, v179
	v_div_fixup_f32 v189, v176, v189, 1.0
	v_and_b32_e32 v190, 15, v197
	v_lshlrev_b32_e32 v190, 2, v190
	v_add_u32_e32 v191, 64, v190
	v_add_u32_e32 v192, 128, v190
	v_add_u32_e32 v193, 192, v190
	ds_bpermute_b32 v244, v190, v188
	ds_bpermute_b32 v245, v190, v189
	ds_bpermute_b32 v246, v191, v188
	ds_bpermute_b32 v247, v191, v189
	ds_bpermute_b32 v248, v192, v188
	ds_bpermute_b32 v249, v192, v189
	ds_bpermute_b32 v250, v193, v188
	ds_bpermute_b32 v251, v193, v189
	s_waitcnt lgkmcnt(0)
	v_ashrrev_i32_e32 v141, 31, v140
	v_lshlrev_b64 v[148:149], 6, v[140:141]
	v_lshl_add_u64 v[160:161], s[30:31], 0, v[148:149]
	s_mov_b32 s27, 0xf800000
	v_lshl_or_b32 v142, s26, 7, v146
	v_ashrrev_i32_e32 v143, 31, v142
	s_movk_i32 s26, 0x1600
	v_mov_b32_e32 v200, v202
	s_waitcnt lgkmcnt(0)
	s_nop 0
	s_nop 0
	s_nop 0
	s_nop 0
	s_nop 0
	s_nop 0
	s_nop 0
	s_nop 1
	s_nop 1
	s_nop 0
	v_mov_b32_e32 v148, v244
	v_pk_mul_f32 v[126:127], v[126:127], v[148:149] op_sel_hi:[1,0]
	v_pk_mul_f32 v[118:119], v[118:119], v[148:149] op_sel_hi:[1,0]
	v_mul_f32_e32 v141, 0xbfb8aa3b, v126
	v_exp_f32_e32 v141, v141
	v_pk_mul_f32 v[120:121], v[120:121], v[148:149] op_sel_hi:[1,0]
	v_pk_mul_f32 v[122:123], v[122:123], v[148:149] op_sel_hi:[1,0]
	v_pk_mul_f32 v[114:115], v[114:115], v[148:149] op_sel_hi:[1,0]
	v_add_f32_e32 v141, 1.0, v141
	v_rcp_f32_e32 v150, v141
	v_mul_f32_e32 v141, 0xbfb8aa3b, v127
	v_exp_f32_e32 v141, v141
	v_pk_mul_f32 v[116:117], v[116:117], v[148:149] op_sel_hi:[1,0]
	v_add_f32_e32 v141, 1.0, v141
	v_rcp_f32_e32 v151, v141
	s_nop 0
	v_pk_mul_f32 v[126:127], v[126:127], v[150:151]
	s_nop 0
	v_pk_mul_f32 v[118:119], v[118:119], v[126:127]
	v_pk_mul_f32 v[126:127], v[128:129], v[148:149] op_sel_hi:[1,0]
	s_nop 0
	v_mul_f32_e32 v128, 0xbfb8aa3b, v126
	v_mul_f32_e32 v129, 0xbfb8aa3b, v127
	v_exp_f32_e32 v128, v128
	v_exp_f32_e32 v129, v129
	v_add_f32_e32 v128, 1.0, v128
	v_add_f32_e32 v129, 1.0, v129
	v_rcp_f32_e32 v128, v128
	v_rcp_f32_e32 v129, v129
	s_nop 0
	v_pk_mul_f32 v[126:127], v[126:127], v[128:129]
	s_nop 0
	v_pk_mul_f32 v[120:121], v[120:121], v[126:127]
	v_mul_f32_e32 v126, 0xbfb8aa3b, v122
	v_mul_f32_e32 v127, 0xbfb8aa3b, v123
	v_exp_f32_e32 v126, v126
	v_exp_f32_e32 v127, v127
	v_add_f32_e32 v126, 1.0, v126
	v_add_f32_e32 v127, 1.0, v127
	v_rcp_f32_e32 v126, v126
	v_rcp_f32_e32 v127, v127
	s_nop 0
	v_pk_mul_f32 v[122:123], v[122:123], v[126:127]
	s_nop 0
	v_pk_mul_f32 v[122:123], v[114:115], v[122:123]
	v_pk_mul_f32 v[114:115], v[124:125], v[148:149] op_sel_hi:[1,0]
	s_nop 0
	v_mul_f32_e32 v124, 0xbfb8aa3b, v114
	v_mul_f32_e32 v125, 0xbfb8aa3b, v115
	v_exp_f32_e32 v124, v124
	v_exp_f32_e32 v125, v125
	v_add_f32_e32 v124, 1.0, v124
	v_add_f32_e32 v125, 1.0, v125
	v_rcp_f32_e32 v124, v124
	v_rcp_f32_e32 v125, v125
	s_nop 0
	v_pk_mul_f32 v[114:115], v[114:115], v[124:125]
	s_nop 0
	v_pk_mul_f32 v[124:125], v[116:117], v[114:115]
	v_cvt_pk_bf16_f32 v114, v118, v119
	v_mov_b64_e32 v[118:119], s[6:7]
	v_cvt_pk_bf16_f32 v115, v120, v121
	v_cvt_pk_bf16_f32 v116, v122, v123
	v_mad_i64_i32 v[122:123], s[0:1], v140, s26, v[118:119]
	v_lshlrev_b64 v[120:121], 1, v[142:143]
	v_cvt_pk_bf16_f32 v117, v124, v125
	v_lshl_add_u64 v[122:123], v[122:123], 0, v[120:121]
	global_store_dwordx4 v[122:123], v[114:117], off
	s_nop 1
	v_or_b32_e32 v114, 16, v140
	v_ashrrev_i32_e32 v115, 31, v114
	v_lshlrev_b64 v[116:117], 6, v[114:115]
	v_lshl_add_u64 v[116:117], s[30:31], 0, v[116:117]
	s_waitcnt lgkmcnt(0)
	s_nop 0
	s_nop 0
	s_nop 0
	s_nop 0
	s_nop 0
	s_nop 0
	s_nop 1
	s_nop 1
	s_nop 0
	v_mov_b32_e32 v116, v245
	v_pk_mul_f32 v[110:111], v[110:111], v[116:117] op_sel_hi:[1,0]
	v_pk_mul_f32 v[102:103], v[102:103], v[116:117] op_sel_hi:[1,0]
	v_mul_f32_e32 v115, 0xbfb8aa3b, v110
	v_exp_f32_e32 v115, v115
	v_pk_mul_f32 v[104:105], v[104:105], v[116:117] op_sel_hi:[1,0]
	v_pk_mul_f32 v[106:107], v[106:107], v[116:117] op_sel_hi:[1,0]
	v_pk_mul_f32 v[98:99], v[98:99], v[116:117] op_sel_hi:[1,0]
	v_add_f32_e32 v115, 1.0, v115
	v_rcp_f32_e32 v122, v115
	v_mul_f32_e32 v115, 0xbfb8aa3b, v111
	v_exp_f32_e32 v115, v115
	v_pk_mul_f32 v[100:101], v[100:101], v[116:117] op_sel_hi:[1,0]
	v_add_f32_e32 v115, 1.0, v115
	v_rcp_f32_e32 v123, v115
	s_nop 0
	v_pk_mul_f32 v[110:111], v[110:111], v[122:123]
	s_nop 0
	v_pk_mul_f32 v[102:103], v[102:103], v[110:111]
	v_pk_mul_f32 v[110:111], v[112:113], v[116:117] op_sel_hi:[1,0]
	s_nop 0
	v_mul_f32_e32 v112, 0xbfb8aa3b, v110
	v_mul_f32_e32 v113, 0xbfb8aa3b, v111
	v_exp_f32_e32 v112, v112
	v_exp_f32_e32 v113, v113
	v_add_f32_e32 v112, 1.0, v112
	v_add_f32_e32 v113, 1.0, v113
	v_rcp_f32_e32 v112, v112
	v_rcp_f32_e32 v113, v113
	s_nop 0
	v_pk_mul_f32 v[110:111], v[110:111], v[112:113]
	s_nop 0
	v_pk_mul_f32 v[104:105], v[104:105], v[110:111]
	v_mul_f32_e32 v110, 0xbfb8aa3b, v106
	v_mul_f32_e32 v111, 0xbfb8aa3b, v107
	v_exp_f32_e32 v110, v110
	v_exp_f32_e32 v111, v111
	v_add_f32_e32 v110, 1.0, v110
	v_add_f32_e32 v111, 1.0, v111
	v_rcp_f32_e32 v110, v110
	v_rcp_f32_e32 v111, v111
	s_nop 0
	v_pk_mul_f32 v[106:107], v[106:107], v[110:111]
	s_nop 0
	v_pk_mul_f32 v[106:107], v[98:99], v[106:107]
	v_pk_mul_f32 v[98:99], v[108:109], v[116:117] op_sel_hi:[1,0]
	s_nop 0
	v_mul_f32_e32 v108, 0xbfb8aa3b, v98
	v_mul_f32_e32 v109, 0xbfb8aa3b, v99
	v_exp_f32_e32 v108, v108
	v_exp_f32_e32 v109, v109
	v_add_f32_e32 v108, 1.0, v108
	v_add_f32_e32 v109, 1.0, v109
	v_rcp_f32_e32 v108, v108
	v_rcp_f32_e32 v109, v109
	s_nop 0
	v_pk_mul_f32 v[98:99], v[98:99], v[108:109]
	s_nop 0
	v_pk_mul_f32 v[108:109], v[100:101], v[98:99]
	v_cvt_pk_bf16_f32 v98, v102, v103
	v_mad_i64_i32 v[102:103], s[0:1], v114, s26, v[118:119]
	v_cvt_pk_bf16_f32 v99, v104, v105
	v_cvt_pk_bf16_f32 v100, v106, v107
	v_cvt_pk_bf16_f32 v101, v108, v109
	v_lshl_add_u64 v[102:103], v[102:103], 0, v[120:121]
	global_store_dwordx4 v[102:103], v[98:101], off
	s_nop 1
	v_or_b32_e32 v98, 32, v140
	v_ashrrev_i32_e32 v99, 31, v98
	v_lshlrev_b64 v[100:101], 6, v[98:99]
	v_lshl_add_u64 v[100:101], s[30:31], 0, v[100:101]
	s_waitcnt lgkmcnt(0)
	s_nop 0
	s_nop 0
	s_nop 0
	s_nop 0
	s_nop 0
	s_nop 0
	s_nop 1
	s_nop 1
	s_nop 0
	v_mov_b32_e32 v100, v246
	v_pk_mul_f32 v[94:95], v[94:95], v[100:101] op_sel_hi:[1,0]
	v_pk_mul_f32 v[86:87], v[86:87], v[100:101] op_sel_hi:[1,0]
	v_mul_f32_e32 v99, 0xbfb8aa3b, v94
	v_exp_f32_e32 v99, v99
	v_pk_mul_f32 v[88:89], v[88:89], v[100:101] op_sel_hi:[1,0]
	v_pk_mul_f32 v[90:91], v[90:91], v[100:101] op_sel_hi:[1,0]
	v_pk_mul_f32 v[82:83], v[82:83], v[100:101] op_sel_hi:[1,0]
	v_add_f32_e32 v99, 1.0, v99
	v_rcp_f32_e32 v102, v99
	v_mul_f32_e32 v99, 0xbfb8aa3b, v95
	v_exp_f32_e32 v99, v99
	v_pk_mul_f32 v[84:85], v[84:85], v[100:101] op_sel_hi:[1,0]
	v_add_f32_e32 v99, 1.0, v99
	v_rcp_f32_e32 v103, v99
	s_nop 0
	v_pk_mul_f32 v[94:95], v[94:95], v[102:103]
	s_nop 0
	v_pk_mul_f32 v[86:87], v[86:87], v[94:95]
	v_pk_mul_f32 v[94:95], v[96:97], v[100:101] op_sel_hi:[1,0]
	s_nop 0
	v_mul_f32_e32 v96, 0xbfb8aa3b, v94
	v_mul_f32_e32 v97, 0xbfb8aa3b, v95
	v_exp_f32_e32 v96, v96
	v_exp_f32_e32 v97, v97
	v_add_f32_e32 v96, 1.0, v96
	v_add_f32_e32 v97, 1.0, v97
	v_rcp_f32_e32 v96, v96
	v_rcp_f32_e32 v97, v97
	s_nop 0
	v_pk_mul_f32 v[94:95], v[94:95], v[96:97]
	s_nop 0
	v_pk_mul_f32 v[88:89], v[88:89], v[94:95]
	v_mul_f32_e32 v94, 0xbfb8aa3b, v90
	v_mul_f32_e32 v95, 0xbfb8aa3b, v91
	v_exp_f32_e32 v94, v94
	v_exp_f32_e32 v95, v95
	v_add_f32_e32 v94, 1.0, v94
	v_add_f32_e32 v95, 1.0, v95
	v_rcp_f32_e32 v94, v94
	v_rcp_f32_e32 v95, v95
	s_nop 0
	v_pk_mul_f32 v[90:91], v[90:91], v[94:95]
	s_nop 0
	v_pk_mul_f32 v[90:91], v[82:83], v[90:91]
	v_pk_mul_f32 v[82:83], v[92:93], v[100:101] op_sel_hi:[1,0]
	s_nop 0
	v_mul_f32_e32 v92, 0xbfb8aa3b, v82
	v_mul_f32_e32 v93, 0xbfb8aa3b, v83
	v_exp_f32_e32 v92, v92
	v_exp_f32_e32 v93, v93
	v_add_f32_e32 v92, 1.0, v92
	v_add_f32_e32 v93, 1.0, v93
	v_rcp_f32_e32 v92, v92
	v_rcp_f32_e32 v93, v93
	s_nop 0
	v_pk_mul_f32 v[82:83], v[82:83], v[92:93]
	s_nop 0
	v_pk_mul_f32 v[92:93], v[84:85], v[82:83]
	v_cvt_pk_bf16_f32 v82, v86, v87
	v_mad_i64_i32 v[86:87], s[0:1], v98, s26, v[118:119]
	v_cvt_pk_bf16_f32 v83, v88, v89
	v_cvt_pk_bf16_f32 v84, v90, v91
	v_cvt_pk_bf16_f32 v85, v92, v93
	v_lshl_add_u64 v[86:87], v[86:87], 0, v[120:121]
	global_store_dwordx4 v[86:87], v[82:85], off
	s_nop 1
	v_or_b32_e32 v82, 48, v140
	v_ashrrev_i32_e32 v83, 31, v82
	v_lshlrev_b64 v[84:85], 6, v[82:83]
	v_lshl_add_u64 v[84:85], s[30:31], 0, v[84:85]
	s_waitcnt lgkmcnt(0)
	s_nop 0
	s_nop 0
	s_nop 0
	s_nop 0
	s_nop 0
	s_nop 0
	s_nop 1
	s_nop 1
	s_nop 0
	v_mov_b32_e32 v84, v247
	v_pk_mul_f32 v[78:79], v[78:79], v[84:85] op_sel_hi:[1,0]
	v_pk_mul_f32 v[70:71], v[70:71], v[84:85] op_sel_hi:[1,0]
	v_mul_f32_e32 v83, 0xbfb8aa3b, v78
	v_exp_f32_e32 v83, v83
	v_pk_mul_f32 v[72:73], v[72:73], v[84:85] op_sel_hi:[1,0]
	v_pk_mul_f32 v[74:75], v[74:75], v[84:85] op_sel_hi:[1,0]
	v_pk_mul_f32 v[66:67], v[66:67], v[84:85] op_sel_hi:[1,0]
	v_add_f32_e32 v83, 1.0, v83
	v_rcp_f32_e32 v86, v83
	v_mul_f32_e32 v83, 0xbfb8aa3b, v79
	v_exp_f32_e32 v83, v83
	v_pk_mul_f32 v[68:69], v[68:69], v[84:85] op_sel_hi:[1,0]
	v_add_f32_e32 v83, 1.0, v83
	v_rcp_f32_e32 v87, v83
	s_nop 0
	v_pk_mul_f32 v[78:79], v[78:79], v[86:87]
	s_nop 0
	v_pk_mul_f32 v[70:71], v[70:71], v[78:79]
	v_pk_mul_f32 v[78:79], v[80:81], v[84:85] op_sel_hi:[1,0]
	s_nop 0
	v_mul_f32_e32 v80, 0xbfb8aa3b, v78
	v_mul_f32_e32 v81, 0xbfb8aa3b, v79
	v_exp_f32_e32 v80, v80
	v_exp_f32_e32 v81, v81
	v_add_f32_e32 v80, 1.0, v80
	v_add_f32_e32 v81, 1.0, v81
	v_rcp_f32_e32 v80, v80
	v_rcp_f32_e32 v81, v81
	s_nop 0
	v_pk_mul_f32 v[78:79], v[78:79], v[80:81]
	s_nop 0
	v_pk_mul_f32 v[72:73], v[72:73], v[78:79]
	v_mul_f32_e32 v78, 0xbfb8aa3b, v74
	v_mul_f32_e32 v79, 0xbfb8aa3b, v75
	v_exp_f32_e32 v78, v78
	v_exp_f32_e32 v79, v79
	v_add_f32_e32 v78, 1.0, v78
	v_add_f32_e32 v79, 1.0, v79
	v_rcp_f32_e32 v78, v78
	v_rcp_f32_e32 v79, v79
	s_nop 0
	v_pk_mul_f32 v[74:75], v[74:75], v[78:79]
	s_nop 0
	v_pk_mul_f32 v[74:75], v[66:67], v[74:75]
	v_pk_mul_f32 v[66:67], v[76:77], v[84:85] op_sel_hi:[1,0]
	s_nop 0
	v_mul_f32_e32 v76, 0xbfb8aa3b, v66
	v_mul_f32_e32 v77, 0xbfb8aa3b, v67
	v_exp_f32_e32 v76, v76
	v_exp_f32_e32 v77, v77
	v_add_f32_e32 v76, 1.0, v76
	v_add_f32_e32 v77, 1.0, v77
	v_rcp_f32_e32 v76, v76
	v_rcp_f32_e32 v77, v77
	s_nop 0
	v_pk_mul_f32 v[66:67], v[66:67], v[76:77]
	s_nop 0
	v_pk_mul_f32 v[76:77], v[68:69], v[66:67]
	v_cvt_pk_bf16_f32 v66, v70, v71
	v_mad_i64_i32 v[70:71], s[0:1], v82, s26, v[118:119]
	v_cvt_pk_bf16_f32 v67, v72, v73
	v_cvt_pk_bf16_f32 v68, v74, v75
	v_cvt_pk_bf16_f32 v69, v76, v77
	v_lshl_add_u64 v[70:71], v[70:71], 0, v[120:121]
	global_store_dwordx4 v[70:71], v[66:69], off
	s_nop 1
	v_add_u32_e32 v66, 0x80, v140
	v_ashrrev_i32_e32 v67, 31, v66
	v_lshlrev_b64 v[68:69], 6, v[66:67]
	v_lshl_add_u64 v[68:69], s[30:31], 0, v[68:69]
	s_waitcnt lgkmcnt(0)
	s_nop 0
	s_nop 0
	s_nop 0
	s_nop 0
	s_nop 0
	s_nop 0
	s_nop 1
	s_nop 1
	s_nop 0
	v_mov_b32_e32 v68, v248
	v_pk_mul_f32 v[60:61], v[60:61], v[68:69] op_sel_hi:[1,0]
	v_pk_mul_f32 v[52:53], v[52:53], v[68:69] op_sel_hi:[1,0]
	v_mul_f32_e32 v67, 0xbfb8aa3b, v60
	v_exp_f32_e32 v67, v67
	v_pk_mul_f32 v[54:55], v[54:55], v[68:69] op_sel_hi:[1,0]
	v_pk_mul_f32 v[56:57], v[56:57], v[68:69] op_sel_hi:[1,0]
	v_pk_mul_f32 v[48:49], v[48:49], v[68:69] op_sel_hi:[1,0]
	v_add_f32_e32 v67, 1.0, v67
	v_rcp_f32_e32 v70, v67
	v_mul_f32_e32 v67, 0xbfb8aa3b, v61
	v_exp_f32_e32 v67, v67
	v_pk_mul_f32 v[50:51], v[50:51], v[68:69] op_sel_hi:[1,0]
	v_add_f32_e32 v67, 1.0, v67
	v_rcp_f32_e32 v71, v67
	s_nop 0
	v_pk_mul_f32 v[60:61], v[60:61], v[70:71]
	s_nop 0
	v_pk_mul_f32 v[52:53], v[52:53], v[60:61]
	v_pk_mul_f32 v[60:61], v[62:63], v[68:69] op_sel_hi:[1,0]
	s_nop 0
	v_mul_f32_e32 v62, 0xbfb8aa3b, v60
	v_mul_f32_e32 v63, 0xbfb8aa3b, v61
	v_exp_f32_e32 v62, v62
	v_exp_f32_e32 v63, v63
	v_add_f32_e32 v62, 1.0, v62
	v_add_f32_e32 v63, 1.0, v63
	v_rcp_f32_e32 v62, v62
	v_rcp_f32_e32 v63, v63
	s_nop 0
	v_pk_mul_f32 v[60:61], v[60:61], v[62:63]
	s_nop 0
	v_pk_mul_f32 v[54:55], v[54:55], v[60:61]
	v_mul_f32_e32 v60, 0xbfb8aa3b, v56
	v_mul_f32_e32 v61, 0xbfb8aa3b, v57
	v_exp_f32_e32 v60, v60
	v_exp_f32_e32 v61, v61
	v_add_f32_e32 v60, 1.0, v60
	v_add_f32_e32 v61, 1.0, v61
	v_rcp_f32_e32 v60, v60
	v_rcp_f32_e32 v61, v61
	s_nop 0
	v_pk_mul_f32 v[56:57], v[56:57], v[60:61]
	s_nop 0
	v_pk_mul_f32 v[56:57], v[48:49], v[56:57]
	v_pk_mul_f32 v[48:49], v[58:59], v[68:69] op_sel_hi:[1,0]
	s_nop 0
	v_mul_f32_e32 v58, 0xbfb8aa3b, v48
	v_mul_f32_e32 v59, 0xbfb8aa3b, v49
	v_exp_f32_e32 v58, v58
	v_exp_f32_e32 v59, v59
	v_add_f32_e32 v58, 1.0, v58
	v_add_f32_e32 v59, 1.0, v59
	v_rcp_f32_e32 v58, v58
	v_rcp_f32_e32 v59, v59
	s_nop 0
	v_pk_mul_f32 v[48:49], v[48:49], v[58:59]
	s_nop 0
	v_pk_mul_f32 v[58:59], v[50:51], v[48:49]
	v_cvt_pk_bf16_f32 v48, v52, v53
	v_mad_i64_i32 v[52:53], s[0:1], v66, s26, v[118:119]
	v_cvt_pk_bf16_f32 v49, v54, v55
	v_cvt_pk_bf16_f32 v50, v56, v57
	v_cvt_pk_bf16_f32 v51, v58, v59
	v_lshl_add_u64 v[52:53], v[52:53], 0, v[120:121]
	global_store_dwordx4 v[52:53], v[48:51], off
	s_nop 1
	v_add_u32_e32 v48, 0x90, v140
	v_ashrrev_i32_e32 v49, 31, v48
	v_lshlrev_b64 v[50:51], 6, v[48:49]
	v_lshl_add_u64 v[50:51], s[30:31], 0, v[50:51]
	s_waitcnt lgkmcnt(0)
	s_nop 0
	s_nop 0
	s_nop 0
	s_nop 0
	s_nop 0
	s_nop 0
	s_nop 1
	s_nop 1
	s_nop 0
	v_mov_b32_e32 v50, v249
	v_pk_mul_f32 v[44:45], v[44:45], v[50:51] op_sel_hi:[1,0]
	v_pk_mul_f32 v[36:37], v[36:37], v[50:51] op_sel_hi:[1,0]
	v_mul_f32_e32 v49, 0xbfb8aa3b, v44
	v_exp_f32_e32 v49, v49
	v_pk_mul_f32 v[38:39], v[38:39], v[50:51] op_sel_hi:[1,0]
	v_pk_mul_f32 v[40:41], v[40:41], v[50:51] op_sel_hi:[1,0]
	v_pk_mul_f32 v[32:33], v[32:33], v[50:51] op_sel_hi:[1,0]
	v_add_f32_e32 v49, 1.0, v49
	v_rcp_f32_e32 v52, v49
	v_mul_f32_e32 v49, 0xbfb8aa3b, v45
	v_exp_f32_e32 v49, v49
	v_pk_mul_f32 v[34:35], v[34:35], v[50:51] op_sel_hi:[1,0]
	v_add_f32_e32 v49, 1.0, v49
	v_rcp_f32_e32 v53, v49
	s_nop 0
	v_pk_mul_f32 v[44:45], v[44:45], v[52:53]
	s_nop 0
	v_pk_mul_f32 v[36:37], v[36:37], v[44:45]
	v_pk_mul_f32 v[44:45], v[46:47], v[50:51] op_sel_hi:[1,0]
	s_nop 0
	v_mul_f32_e32 v46, 0xbfb8aa3b, v44
	v_mul_f32_e32 v47, 0xbfb8aa3b, v45
	v_exp_f32_e32 v46, v46
	v_exp_f32_e32 v47, v47
	v_add_f32_e32 v46, 1.0, v46
	v_add_f32_e32 v47, 1.0, v47
	v_rcp_f32_e32 v46, v46
	v_rcp_f32_e32 v47, v47
	s_nop 0
	v_pk_mul_f32 v[44:45], v[44:45], v[46:47]
	s_nop 0
	v_pk_mul_f32 v[38:39], v[38:39], v[44:45]
	v_mul_f32_e32 v44, 0xbfb8aa3b, v40
	v_mul_f32_e32 v45, 0xbfb8aa3b, v41
	v_exp_f32_e32 v44, v44
	v_exp_f32_e32 v45, v45
	v_add_f32_e32 v44, 1.0, v44
	v_add_f32_e32 v45, 1.0, v45
	v_rcp_f32_e32 v44, v44
	v_rcp_f32_e32 v45, v45
	s_nop 0
	v_pk_mul_f32 v[40:41], v[40:41], v[44:45]
	s_nop 0
	v_pk_mul_f32 v[40:41], v[32:33], v[40:41]
	v_pk_mul_f32 v[32:33], v[42:43], v[50:51] op_sel_hi:[1,0]
	s_nop 0
	v_mul_f32_e32 v42, 0xbfb8aa3b, v32
	v_mul_f32_e32 v43, 0xbfb8aa3b, v33
	v_exp_f32_e32 v42, v42
	v_exp_f32_e32 v43, v43
	v_add_f32_e32 v42, 1.0, v42
	v_add_f32_e32 v43, 1.0, v43
	v_rcp_f32_e32 v42, v42
	v_rcp_f32_e32 v43, v43
	s_nop 0
	v_pk_mul_f32 v[32:33], v[32:33], v[42:43]
	s_nop 0
	v_pk_mul_f32 v[42:43], v[34:35], v[32:33]
	v_cvt_pk_bf16_f32 v32, v36, v37
	v_mad_i64_i32 v[36:37], s[0:1], v48, s26, v[118:119]
	v_cvt_pk_bf16_f32 v33, v38, v39
	v_cvt_pk_bf16_f32 v34, v40, v41
	v_cvt_pk_bf16_f32 v35, v42, v43
	v_lshl_add_u64 v[36:37], v[36:37], 0, v[120:121]
	global_store_dwordx4 v[36:37], v[32:35], off
	s_nop 1
	v_add_u32_e32 v32, 0xa0, v140
	v_ashrrev_i32_e32 v33, 31, v32
	v_lshlrev_b64 v[34:35], 6, v[32:33]
	v_lshl_add_u64 v[34:35], s[30:31], 0, v[34:35]
	s_waitcnt lgkmcnt(0)
	s_nop 0
	s_nop 0
	s_nop 0
	s_nop 0
	s_nop 0
	s_nop 0
	s_nop 1
	s_nop 1
	s_nop 0
	v_mov_b32_e32 v34, v250
	v_pk_mul_f32 v[28:29], v[28:29], v[34:35] op_sel_hi:[1,0]
	v_pk_mul_f32 v[20:21], v[20:21], v[34:35] op_sel_hi:[1,0]
	v_mul_f32_e32 v33, 0xbfb8aa3b, v28
	v_exp_f32_e32 v33, v33
	v_pk_mul_f32 v[22:23], v[22:23], v[34:35] op_sel_hi:[1,0]
	v_pk_mul_f32 v[24:25], v[24:25], v[34:35] op_sel_hi:[1,0]
	v_pk_mul_f32 v[16:17], v[16:17], v[34:35] op_sel_hi:[1,0]
	v_add_f32_e32 v33, 1.0, v33
	v_rcp_f32_e32 v36, v33
	v_mul_f32_e32 v33, 0xbfb8aa3b, v29
	v_exp_f32_e32 v33, v33
	v_pk_mul_f32 v[18:19], v[18:19], v[34:35] op_sel_hi:[1,0]
	v_add_f32_e32 v33, 1.0, v33
	v_rcp_f32_e32 v37, v33
	s_nop 0
	v_pk_mul_f32 v[28:29], v[28:29], v[36:37]
	s_nop 0
	v_pk_mul_f32 v[20:21], v[20:21], v[28:29]
	v_pk_mul_f32 v[28:29], v[30:31], v[34:35] op_sel_hi:[1,0]
	s_nop 0
	v_mul_f32_e32 v30, 0xbfb8aa3b, v28
	v_mul_f32_e32 v31, 0xbfb8aa3b, v29
	v_exp_f32_e32 v30, v30
	v_exp_f32_e32 v31, v31
	v_add_f32_e32 v30, 1.0, v30
	v_add_f32_e32 v31, 1.0, v31
	v_rcp_f32_e32 v30, v30
	v_rcp_f32_e32 v31, v31
	s_nop 0
	v_pk_mul_f32 v[28:29], v[28:29], v[30:31]
	s_nop 0
	v_pk_mul_f32 v[22:23], v[22:23], v[28:29]
	v_mul_f32_e32 v28, 0xbfb8aa3b, v24
	v_mul_f32_e32 v29, 0xbfb8aa3b, v25
	v_exp_f32_e32 v28, v28
	v_exp_f32_e32 v29, v29
	v_add_f32_e32 v28, 1.0, v28
	v_add_f32_e32 v29, 1.0, v29
	v_rcp_f32_e32 v28, v28
	v_rcp_f32_e32 v29, v29
	s_nop 0
	v_pk_mul_f32 v[24:25], v[24:25], v[28:29]
	s_nop 0
	v_pk_mul_f32 v[24:25], v[16:17], v[24:25]
	v_pk_mul_f32 v[16:17], v[26:27], v[34:35] op_sel_hi:[1,0]
	s_nop 0
	v_mul_f32_e32 v26, 0xbfb8aa3b, v16
	v_mul_f32_e32 v27, 0xbfb8aa3b, v17
	v_exp_f32_e32 v26, v26
	v_exp_f32_e32 v27, v27
	v_add_f32_e32 v26, 1.0, v26
	v_add_f32_e32 v27, 1.0, v27
	v_rcp_f32_e32 v26, v26
	v_rcp_f32_e32 v27, v27
	s_nop 0
	v_pk_mul_f32 v[16:17], v[16:17], v[26:27]
	s_nop 0
	v_pk_mul_f32 v[26:27], v[18:19], v[16:17]
	v_cvt_pk_bf16_f32 v16, v20, v21
	v_mad_i64_i32 v[20:21], s[0:1], v32, s26, v[118:119]
	v_cvt_pk_bf16_f32 v17, v22, v23
	v_cvt_pk_bf16_f32 v18, v24, v25
	v_cvt_pk_bf16_f32 v19, v26, v27
	v_lshl_add_u64 v[20:21], v[20:21], 0, v[120:121]
	global_store_dwordx4 v[20:21], v[16:19], off
	s_nop 1
	v_add_u32_e32 v16, 0xb0, v140
	v_ashrrev_i32_e32 v17, 31, v16
	v_lshlrev_b64 v[18:19], 6, v[16:17]
	v_lshl_add_u64 v[18:19], s[30:31], 0, v[18:19]
	s_waitcnt lgkmcnt(0)
	s_nop 0
	s_nop 0
	s_nop 0
	s_nop 0
	s_nop 0
	s_nop 0
	s_nop 1
	s_nop 1
	s_nop 0
	v_mov_b32_e32 v18, v251
	v_pk_mul_f32 v[12:13], v[12:13], v[18:19] op_sel_hi:[1,0]
	v_pk_mul_f32 v[4:5], v[4:5], v[18:19] op_sel_hi:[1,0]
	v_mul_f32_e32 v17, 0xbfb8aa3b, v12
	v_exp_f32_e32 v17, v17
	v_pk_mul_f32 v[6:7], v[6:7], v[18:19] op_sel_hi:[1,0]
	v_pk_mul_f32 v[8:9], v[8:9], v[18:19] op_sel_hi:[1,0]
	v_pk_mul_f32 v[0:1], v[0:1], v[18:19] op_sel_hi:[1,0]
	v_add_f32_e32 v17, 1.0, v17
	v_rcp_f32_e32 v20, v17
	v_mul_f32_e32 v17, 0xbfb8aa3b, v13
	v_exp_f32_e32 v17, v17
	v_pk_mul_f32 v[2:3], v[2:3], v[18:19] op_sel_hi:[1,0]
	s_andn2_b64 vcc, exec, s[38:39]
	v_add_f32_e32 v17, 1.0, v17
	v_rcp_f32_e32 v21, v17
	s_nop 0
	v_pk_mul_f32 v[12:13], v[12:13], v[20:21]
	s_nop 0
	v_pk_mul_f32 v[4:5], v[4:5], v[12:13]
	v_pk_mul_f32 v[12:13], v[14:15], v[18:19] op_sel_hi:[1,0]
	s_nop 0
	v_mul_f32_e32 v14, 0xbfb8aa3b, v12
	v_mul_f32_e32 v15, 0xbfb8aa3b, v13
	v_exp_f32_e32 v14, v14
	v_exp_f32_e32 v15, v15
	v_add_f32_e32 v14, 1.0, v14
	v_add_f32_e32 v15, 1.0, v15
	v_rcp_f32_e32 v14, v14
	v_rcp_f32_e32 v15, v15
	s_nop 0
	v_pk_mul_f32 v[12:13], v[12:13], v[14:15]
	s_nop 0
	v_pk_mul_f32 v[6:7], v[6:7], v[12:13]
	v_mul_f32_e32 v12, 0xbfb8aa3b, v8
	v_mul_f32_e32 v13, 0xbfb8aa3b, v9
	v_exp_f32_e32 v12, v12
	v_exp_f32_e32 v13, v13
	v_add_f32_e32 v12, 1.0, v12
	v_add_f32_e32 v13, 1.0, v13
	v_rcp_f32_e32 v12, v12
	v_rcp_f32_e32 v13, v13
	s_nop 0
	v_pk_mul_f32 v[8:9], v[8:9], v[12:13]
	s_nop 0
	v_pk_mul_f32 v[8:9], v[0:1], v[8:9]
	v_pk_mul_f32 v[0:1], v[10:11], v[18:19] op_sel_hi:[1,0]
	s_nop 0
	v_mul_f32_e32 v10, 0xbfb8aa3b, v0
	v_mul_f32_e32 v11, 0xbfb8aa3b, v1
	v_exp_f32_e32 v10, v10
	v_exp_f32_e32 v11, v11
	v_add_f32_e32 v10, 1.0, v10
	v_add_f32_e32 v11, 1.0, v11
	v_rcp_f32_e32 v10, v10
	v_rcp_f32_e32 v11, v11
	s_nop 0
	v_pk_mul_f32 v[0:1], v[0:1], v[10:11]
	s_nop 0
	v_pk_mul_f32 v[10:11], v[2:3], v[0:1]
	v_cvt_pk_bf16_f32 v0, v4, v5
	v_mad_i64_i32 v[4:5], s[0:1], v16, s26, v[118:119]
	v_cvt_pk_bf16_f32 v1, v6, v7
	v_cvt_pk_bf16_f32 v2, v8, v9
	v_cvt_pk_bf16_f32 v3, v10, v11
	v_lshl_add_u64 v[4:5], v[4:5], 0, v[120:121]
	s_mov_b64 s[0:1], -1
	global_store_dwordx4 v[4:5], v[0:3], off
	s_cbranch_vccnz .LBB0_1248
	s_andn2_b64 vcc, exec, s[4:5]
	s_cbranch_vccnz .LBB0_1247
	s_barrier
	s_branch .LBB0_1247
